# spatial-gating phase: all ~42 global loads of an item issued together at the top of the iteration (prefetch registers), the serialised load/wait ladder replaced by register moves
# baseline (speedup 1.0000x reference)
.LBB0_688:
	s_and_b32 s33, s3, 0xffffff80
	v_mov_b32_e32 v71, v61
	v_mov_b32_e32 v73, v61
	v_mov_b32_e32 v75, v61
	v_mov_b32_e32 v77, v61
	v_or_b32_e32 v252, s33, v80
	v_ashrrev_i32_e32 v253, 31, v252
	v_lshl_add_u64 v[252:253], v[252:253], 2, s[4:5]
	global_load_dwordx4 v[0:3], v[252:253], off
	s_and_b32 s98, s87, 7
	s_lshl_b32 s99, s98, 14
	v_mov_b32_e32 v217, 0
	v_or_b32_e32 v216, s99, v83
	v_lshlrev_b32_e32 v216, 2, v216
	v_lshl_add_u64 v[252:253], v[62:63], 0, v[216:217]
	global_load_dwordx4 v[8:11], v[252:253], off
	v_or_b32_e32 v216, s99, v84
	v_lshlrev_b32_e32 v216, 2, v216
	v_lshl_add_u64 v[252:253], v[62:63], 0, v[216:217]
	global_load_dwordx4 v[12:15], v[252:253], off
	v_or_b32_e32 v216, s99, v85
	v_lshlrev_b32_e32 v216, 2, v216
	v_lshl_add_u64 v[252:253], v[62:63], 0, v[216:217]
	global_load_dwordx4 v[16:19], v[252:253], off
	v_or_b32_e32 v216, s99, v86
	v_lshlrev_b32_e32 v216, 2, v216
	v_lshl_add_u64 v[252:253], v[62:63], 0, v[216:217]
	global_load_dwordx4 v[20:23], v[252:253], off
	v_or_b32_e32 v216, s99, v87
	v_lshlrev_b32_e32 v216, 2, v216
	v_lshl_add_u64 v[252:253], v[62:63], 0, v[216:217]
	global_load_dwordx4 v[24:27], v[252:253], off
	v_or_b32_e32 v216, s99, v88
	v_lshlrev_b32_e32 v216, 2, v216
	v_lshl_add_u64 v[252:253], v[62:63], 0, v[216:217]
	global_load_dwordx4 v[28:31], v[252:253], off
	v_or_b32_e32 v216, s99, v89
	v_lshlrev_b32_e32 v216, 2, v216
	v_lshl_add_u64 v[252:253], v[62:63], 0, v[216:217]
	global_load_dwordx4 v[32:35], v[252:253], off
	v_add_lshl_u32 v216, s99, v90, 2
	v_lshl_add_u64 v[252:253], v[62:63], 0, v[216:217]
	global_load_dwordx4 v[36:39], v[252:253], off
	v_or_b32_e32 v252, s33, v81
	v_ashrrev_i32_e32 v253, 31, v252
	v_lshlrev_b64 v[252:253], 13, v[252:253]
	v_lshl_add_u64 v[252:253], s[96:97], 0, v[252:253]
	s_lshl_b32 s100, s98, 9
	s_mov_b32 s101, 0
	v_lshl_add_u64 v[252:253], v[252:253], 0, s[100:101]
	s_add_u32 s100, s96, s100
	s_addc_u32 s101, s97, 0
	s_mov_b64 s[98:99], 0x1000
	v_lshl_add_u64 v[252:253], v[252:253], 0, s[98:99]
	v_lshl_add_u64 v[216:217], v[252:253], 0, v[66:67]
	global_load_dwordx4 v[40:43], v[216:217], off
	v_lshl_add_u64 v[214:215], v[252:253], 0, v[68:69]
	global_load_dwordx4 v[44:47], v[214:215], off
	global_load_dwordx4 v[48:51], v[216:217], off offset:128
	v_lshl_add_u64 v[214:215], v[252:253], 0, v[70:71]
	global_load_dwordx4 v[52:55], v[214:215], off
	global_load_dwordx4 v[56:59], v[216:217], off offset:256
	v_lshl_add_u64 v[214:215], v[252:253], 0, v[72:73]
	global_load_dwordx4 v[164:167], v[214:215], off
	global_load_dwordx4 v[168:171], v[216:217], off offset:384
	v_lshl_add_u64 v[214:215], v[252:253], 0, v[74:75]
	global_load_dwordx4 v[172:175], v[214:215], off
	s_and_b32 s98, s87, 7
	s_lshl_b32 s99, s98, 7
	v_add_lshl_u32 v231, s99, v82, 2
	global_load_dword v234, v231, s[74:75]
	global_load_dword v235, v231, s[74:75] offset:64
	global_load_dword v237, v231, s[74:75] offset:128
	global_load_dword v228, v231, s[74:75] offset:192
	v_add_u32_e32 v252, s33, v82
	v_ashrrev_i32_e32 v253, 31, v252
	v_lshlrev_b64 v[252:253], 13, v[252:253]
	v_lshl_add_u64 v[252:253], s[100:101], 0, v[252:253]
	v_lshl_add_u64 v[252:253], v[252:253], 0, v[76:77]
	global_load_dwordx2 v[184:185], v[252:253], off
	global_load_dwordx2 v[186:187], v[252:253], off offset:32
	global_load_dwordx2 v[188:189], v[252:253], off offset:64
	global_load_dwordx2 v[190:191], v[252:253], off offset:96
	v_add_u32_e32 v252, s33, v99
	v_ashrrev_i32_e32 v253, 31, v252
	v_lshlrev_b64 v[252:253], 13, v[252:253]
	v_lshl_add_u64 v[252:253], s[100:101], 0, v[252:253]
	v_lshl_add_u64 v[252:253], v[252:253], 0, v[76:77]
	global_load_dwordx2 v[192:193], v[252:253], off
	global_load_dwordx2 v[194:195], v[252:253], off offset:32
	global_load_dwordx2 v[196:197], v[252:253], off offset:64
	global_load_dwordx2 v[198:199], v[252:253], off offset:96
	v_add_u32_e32 v252, s33, v100
	v_ashrrev_i32_e32 v253, 31, v252
	v_lshlrev_b64 v[252:253], 13, v[252:253]
	v_lshl_add_u64 v[252:253], s[100:101], 0, v[252:253]
	v_lshl_add_u64 v[252:253], v[252:253], 0, v[76:77]
	global_load_dwordx2 v[200:201], v[252:253], off
	global_load_dwordx2 v[202:203], v[252:253], off offset:32
	global_load_dwordx2 v[204:205], v[252:253], off offset:64
	global_load_dwordx2 v[206:207], v[252:253], off offset:96
	v_add_u32_e32 v252, s33, v101
	v_ashrrev_i32_e32 v253, 31, v252
	v_lshlrev_b64 v[252:253], 13, v[252:253]
	v_lshl_add_u64 v[252:253], s[100:101], 0, v[252:253]
	v_lshl_add_u64 v[252:253], v[252:253], 0, v[76:77]
	global_load_dwordx2 v[208:209], v[252:253], off
	global_load_dwordx2 v[210:211], v[252:253], off offset:32
	global_load_dwordx2 v[212:213], v[252:253], off offset:64
	global_load_dwordx2 v[214:215], v[252:253], off offset:96
	s_lshl_b32 s98, s98, 10
	s_mov_b32 s99, 0
	v_lshl_add_u64 v[252:253], v[64:65], 0, s[98:99]
	global_load_dwordx4 v[240:243], v[252:253], off
	global_load_dwordx4 v[244:247], v[252:253], off offset:64
	global_load_dwordx4 v[248:251], v[252:253], off offset:128
	global_load_dwordx2 v[216:217], v[252:253], off offset:192
	global_load_dwordx2 v[252:253], v[252:253], off offset:200
	s_and_b32 s76, s87, 7
	s_lshl_b32 s0, s76, 14
	s_lshl_b32 s72, s76, 9
	v_mov_b32_e32 v71, v61
	v_mov_b32_e32 v73, v61
	v_mov_b32_e32 v75, v61
	s_lshl_b32 s79, s76, 7
	v_mov_b32_e32 v77, v61
	s_waitcnt vmcnt(41)
	v_fmamk_f32 v0, v0, 0x3a000000, v102
	v_rsq_f32_e32 v4, v0
	v_fmamk_f32 v0, v1, 0x3a000000, v102
	v_rsq_f32_e32 v5, v0
	v_fmamk_f32 v0, v2, 0x3a000000, v102
	v_rsq_f32_e32 v6, v0
	v_fmamk_f32 v0, v3, 0x3a000000, v102
	v_rsq_f32_e32 v7, v0
	v_or_b32_e32 v0, s0, v83
	v_lshlrev_b32_e32 v60, 2, v0
	v_lshl_add_u64 v[0:1], v[62:63], 0, v[60:61]
	s_waitcnt vmcnt(40)
	v_mov_b32_e32 v0, v8
	v_mov_b32_e32 v1, v9
	v_mov_b32_e32 v2, v10
	v_mov_b32_e32 v3, v11
	v_mul_f32_e32 v0, v4, v0
	v_cndmask_b32_e64 v0, v0, 0, vcc
	v_mul_f32_e32 v1, v5, v1
	v_cndmask_b32_e64 v1, 0, v1, s[6:7]
	v_mul_f32_e32 v2, v2, v6
	v_mul_f32_e32 v3, v3, v7
	v_cvt_pk_bf16_f32 v0, v0, v1
	v_cndmask_b32_e64 v2, v2, 0, s[8:9]
	v_cndmask_b32_e64 v3, v3, 0, s[10:11]
	v_cvt_pk_bf16_f32 v1, v2, v3
	ds_write_b64 v103, v[0:1]
	v_or_b32_e32 v0, s0, v84
	v_lshlrev_b32_e32 v60, 2, v0
	v_lshl_add_u64 v[0:1], v[62:63], 0, v[60:61]
	s_waitcnt vmcnt(39)
	v_mov_b32_e32 v0, v12
	v_mov_b32_e32 v1, v13
	v_mov_b32_e32 v2, v14
	v_mov_b32_e32 v3, v15
	v_mul_f32_e32 v0, v4, v0
	v_cndmask_b32_e64 v0, v0, 0, s[12:13]
	v_mul_f32_e32 v1, v5, v1
	v_cndmask_b32_e64 v1, 0, v1, s[14:15]
	v_mul_f32_e32 v2, v6, v2
	v_mul_f32_e32 v3, v7, v3
	v_cvt_pk_bf16_f32 v0, v0, v1
	v_cndmask_b32_e64 v2, v2, 0, s[16:17]
	v_cndmask_b32_e64 v3, v3, 0, s[18:19]
	v_cvt_pk_bf16_f32 v1, v2, v3
	ds_write_b64 v103, v[0:1] offset:4352
	v_or_b32_e32 v0, s0, v85
	v_lshlrev_b32_e32 v60, 2, v0
	v_lshl_add_u64 v[0:1], v[62:63], 0, v[60:61]
	s_waitcnt vmcnt(38)
	v_mov_b32_e32 v0, v16
	v_mov_b32_e32 v1, v17
	v_mov_b32_e32 v2, v18
	v_mov_b32_e32 v3, v19
	v_mul_f32_e32 v0, v4, v0
	v_cndmask_b32_e64 v0, v0, 0, s[20:21]
	v_mul_f32_e32 v1, v5, v1
	v_cndmask_b32_e64 v1, 0, v1, s[22:23]
	v_mul_f32_e32 v2, v6, v2
	v_mul_f32_e32 v3, v7, v3
	v_cvt_pk_bf16_f32 v0, v0, v1
	v_cndmask_b32_e64 v2, v2, 0, s[24:25]
	v_cndmask_b32_e64 v3, v3, 0, s[26:27]
	v_cvt_pk_bf16_f32 v1, v2, v3
	ds_write_b64 v103, v[0:1] offset:8704
	v_or_b32_e32 v0, s0, v86
	v_lshlrev_b32_e32 v60, 2, v0
	v_lshl_add_u64 v[0:1], v[62:63], 0, v[60:61]
	s_waitcnt vmcnt(37)
	v_mov_b32_e32 v0, v20
	v_mov_b32_e32 v1, v21
	v_mov_b32_e32 v2, v22
	v_mov_b32_e32 v3, v23
	v_mul_f32_e32 v0, v4, v0
	v_cndmask_b32_e64 v0, v0, 0, s[28:29]
	v_mul_f32_e32 v1, v5, v1
	v_cndmask_b32_e64 v1, 0, v1, s[30:31]
	v_mul_f32_e32 v2, v6, v2
	v_mul_f32_e32 v3, v7, v3
	v_cvt_pk_bf16_f32 v0, v0, v1
	v_cndmask_b32_e64 v2, v2, 0, s[34:35]
	v_cndmask_b32_e64 v3, v3, 0, s[36:37]
	v_cvt_pk_bf16_f32 v1, v2, v3
	ds_write_b64 v103, v[0:1] offset:13056
	v_or_b32_e32 v0, s0, v87
	v_lshlrev_b32_e32 v60, 2, v0
	v_lshl_add_u64 v[0:1], v[62:63], 0, v[60:61]
	s_waitcnt vmcnt(36)
	v_mov_b32_e32 v0, v24
	v_mov_b32_e32 v1, v25
	v_mov_b32_e32 v2, v26
	v_mov_b32_e32 v3, v27
	v_mul_f32_e32 v0, v4, v0
	v_cndmask_b32_e64 v0, v0, 0, s[38:39]
	v_mul_f32_e32 v1, v5, v1
	v_cndmask_b32_e64 v1, 0, v1, s[40:41]
	v_mul_f32_e32 v2, v6, v2
	v_mul_f32_e32 v3, v7, v3
	v_cvt_pk_bf16_f32 v0, v0, v1
	v_cndmask_b32_e64 v2, v2, 0, s[42:43]
	v_cndmask_b32_e64 v3, v3, 0, s[44:45]
	v_cvt_pk_bf16_f32 v1, v2, v3
	ds_write_b64 v103, v[0:1] offset:17408
	v_or_b32_e32 v0, s0, v88
	v_lshlrev_b32_e32 v60, 2, v0
	v_lshl_add_u64 v[0:1], v[62:63], 0, v[60:61]
	s_waitcnt vmcnt(35)
	v_mov_b32_e32 v0, v28
	v_mov_b32_e32 v1, v29
	v_mov_b32_e32 v2, v30
	v_mov_b32_e32 v3, v31
	v_mul_f32_e32 v0, v4, v0
	v_cndmask_b32_e64 v0, v0, 0, s[46:47]
	v_mul_f32_e32 v1, v5, v1
	v_cndmask_b32_e64 v1, 0, v1, s[48:49]
	v_mul_f32_e32 v2, v6, v2
	v_mul_f32_e32 v3, v7, v3
	v_cvt_pk_bf16_f32 v0, v0, v1
	v_cndmask_b32_e64 v2, v2, 0, s[50:51]
	v_cndmask_b32_e64 v3, v3, 0, s[52:53]
	v_cvt_pk_bf16_f32 v1, v2, v3
	ds_write_b64 v103, v[0:1] offset:21760
	v_or_b32_e32 v0, s0, v89
	v_lshlrev_b32_e32 v60, 2, v0
	v_lshl_add_u64 v[0:1], v[62:63], 0, v[60:61]
	v_add_lshl_u32 v60, s0, v90, 2
	s_mov_b64 s[0:1], 0x1000
	s_waitcnt vmcnt(34)
	v_mov_b32_e32 v0, v32
	v_mov_b32_e32 v1, v33
	v_mov_b32_e32 v2, v34
	v_mov_b32_e32 v3, v35
	v_mul_f32_e32 v0, v4, v0
	v_mul_f32_e32 v1, v5, v1
	v_cndmask_b32_e64 v0, v0, 0, s[54:55]
	v_cndmask_b32_e64 v1, 0, v1, s[56:57]
	v_mul_f32_e32 v2, v6, v2
	v_mul_f32_e32 v3, v7, v3
	v_cndmask_b32_e64 v2, v2, 0, s[58:59]
	v_cndmask_b32_e64 v3, v3, 0, s[60:61]
	v_cvt_pk_bf16_f32 v0, v0, v1
	v_cvt_pk_bf16_f32 v1, v2, v3
	ds_write_b64 v103, v[0:1] offset:26112
	v_lshl_add_u64 v[0:1], v[62:63], 0, v[60:61]
	v_add_lshl_u32 v60, s79, v82, 2
	s_waitcnt vmcnt(33)
	v_mov_b32_e32 v0, v36
	v_mov_b32_e32 v1, v37
	v_mov_b32_e32 v2, v38
	v_mov_b32_e32 v3, v39
	v_mul_f32_e32 v0, v4, v0
	v_cndmask_b32_e64 v0, v0, 0, s[62:63]
	v_mul_f32_e32 v1, v5, v1
	v_cndmask_b32_e64 v1, 0, v1, s[64:65]
	v_mul_f32_e32 v2, v6, v2
	v_mul_f32_e32 v3, v7, v3
	v_cvt_pk_bf16_f32 v0, v0, v1
	v_cndmask_b32_e64 v2, v2, 0, s[66:67]
	v_cndmask_b32_e64 v3, v3, 0, s[68:69]
	v_cvt_pk_bf16_f32 v1, v2, v3
	ds_write_b64 v103, v[0:1] offset:30464
	v_or_b32_e32 v0, s33, v81
	v_ashrrev_i32_e32 v1, 31, v0
	v_lshlrev_b64 v[0:1], 13, v[0:1]
	v_lshl_add_u64 v[0:1], s[96:97], 0, v[0:1]
	v_lshl_add_u64 v[0:1], v[0:1], 0, s[72:73]
	v_lshl_add_u64 v[0:1], v[0:1], 0, s[0:1]
	v_lshl_add_u64 v[2:3], v[0:1], 0, v[66:67]
	s_add_u32 s0, s96, s72
	s_addc_u32 s1, s97, 0
	s_lshl_b32 s72, s76, 10
	v_lshl_add_u64 v[78:79], v[64:65], 0, s[72:73]
	s_add_i32 s87, s87, s94
	s_add_i32 s3, s3, s86
	s_cmpk_lt_i32 s87, 0x400
	s_waitcnt vmcnt(32)
	v_mov_b32_e32 v4, v40
	v_mov_b32_e32 v5, v41
	v_mov_b32_e32 v6, v42
	v_mov_b32_e32 v7, v43
	ds_write_b16 v91, v4 offset:34816
	ds_write_b16_d16_hi v91, v4 offset:35088
	ds_write_b16 v91, v5 offset:35360
	ds_write_b16_d16_hi v91, v5 offset:35632
	ds_write_b16 v91, v6 offset:35904
	ds_write_b16_d16_hi v91, v6 offset:36176
	ds_write_b16 v91, v7 offset:36448
	ds_write_b16_d16_hi v91, v7 offset:36720
	v_lshl_add_u64 v[4:5], v[0:1], 0, v[68:69]
	s_waitcnt vmcnt(31)
	v_mov_b32_e32 v4, v44
	v_mov_b32_e32 v5, v45
	v_mov_b32_e32 v6, v46
	v_mov_b32_e32 v7, v47
	ds_write_b16 v92, v4 offset:34816
	ds_write_b16_d16_hi v92, v4 offset:35088
	ds_write_b16 v92, v5 offset:35360
	ds_write_b16_d16_hi v92, v5 offset:35632
	ds_write_b16 v92, v6 offset:35904
	ds_write_b16_d16_hi v92, v6 offset:36176
	ds_write_b16 v92, v7 offset:36448
	ds_write_b16_d16_hi v92, v7 offset:36720
	s_waitcnt vmcnt(30)
	v_mov_b32_e32 v4, v48
	v_mov_b32_e32 v5, v49
	v_mov_b32_e32 v6, v50
	v_mov_b32_e32 v7, v51
	ds_write_b16 v93, v4 offset:34816
	ds_write_b16_d16_hi v93, v4 offset:35088
	ds_write_b16 v91, v5 offset:52768
	ds_write_b16_d16_hi v91, v5 offset:53040
	ds_write_b16 v91, v6 offset:53312
	ds_write_b16_d16_hi v91, v6 offset:53584
	ds_write_b16 v91, v7 offset:53856
	ds_write_b16_d16_hi v91, v7 offset:54128
	v_lshl_add_u64 v[4:5], v[0:1], 0, v[70:71]
	s_waitcnt vmcnt(29)
	v_mov_b32_e32 v4, v52
	v_mov_b32_e32 v5, v53
	v_mov_b32_e32 v6, v54
	v_mov_b32_e32 v7, v55
	ds_write_b16 v94, v4 offset:34816
	ds_write_b16_d16_hi v94, v4 offset:35088
	ds_write_b16 v94, v5 offset:35360
	ds_write_b16_d16_hi v94, v5 offset:35632
	ds_write_b16 v94, v6 offset:35904
	ds_write_b16_d16_hi v94, v6 offset:36176
	ds_write_b16 v94, v7 offset:36448
	ds_write_b16_d16_hi v94, v7 offset:36720
	s_waitcnt vmcnt(28)
	v_mov_b32_e32 v4, v56
	v_mov_b32_e32 v5, v57
	v_mov_b32_e32 v6, v58
	v_mov_b32_e32 v7, v59
	ds_write_b16 v95, v4 offset:34816
	ds_write_b16_d16_hi v95, v4 offset:35088
	ds_write_b16 v95, v5 offset:35360
	ds_write_b16_d16_hi v95, v5 offset:35632
	ds_write_b16 v95, v6 offset:35904
	ds_write_b16_d16_hi v95, v6 offset:36176
	ds_write_b16 v95, v7 offset:36448
	ds_write_b16_d16_hi v95, v7 offset:36720
	v_lshl_add_u64 v[4:5], v[0:1], 0, v[72:73]
	v_lshl_add_u64 v[0:1], v[0:1], 0, v[74:75]
	s_waitcnt vmcnt(27)
	v_mov_b32_e32 v4, v164
	v_mov_b32_e32 v5, v165
	v_mov_b32_e32 v6, v166
	v_mov_b32_e32 v7, v167
	ds_write_b16 v96, v4 offset:34816
	ds_write_b16_d16_hi v96, v4 offset:35088
	ds_write_b16 v96, v5 offset:35360
	ds_write_b16_d16_hi v96, v5 offset:35632
	ds_write_b16 v96, v6 offset:35904
	ds_write_b16_d16_hi v96, v6 offset:36176
	ds_write_b16 v96, v7 offset:36448
	ds_write_b16_d16_hi v96, v7 offset:36720
	s_waitcnt vmcnt(26)
	v_mov_b32_e32 v2, v168
	v_mov_b32_e32 v3, v169
	v_mov_b32_e32 v4, v170
	v_mov_b32_e32 v5, v171
	ds_write_b16 v97, v2 offset:34816
	ds_write_b16_d16_hi v97, v2 offset:35088
	ds_write_b16 v95, v3 offset:52768
	ds_write_b16_d16_hi v95, v3 offset:53040
	ds_write_b16 v95, v4 offset:53312
	ds_write_b16_d16_hi v95, v4 offset:53584
	ds_write_b16 v95, v5 offset:53856
	ds_write_b16_d16_hi v95, v5 offset:54128
	s_waitcnt vmcnt(25)
	v_mov_b32_e32 v0, v172
	v_mov_b32_e32 v1, v173
	v_mov_b32_e32 v2, v174
	v_mov_b32_e32 v3, v175
	ds_write_b16 v98, v0 offset:34816
	ds_write_b16_d16_hi v98, v0 offset:35088
	ds_write_b16 v98, v1 offset:35360
	ds_write_b16_d16_hi v98, v1 offset:35632
	ds_write_b16 v98, v2 offset:35904
	ds_write_b16_d16_hi v98, v2 offset:36176
	ds_write_b16 v98, v3 offset:36448
	ds_write_b16_d16_hi v98, v3 offset:36720
	s_waitcnt lgkmcnt(0)
	s_barrier
	ds_read_b128 v[0:3], v104
	ds_read_b128 v[4:7], v104 offset:4352
	ds_read_b128 v[8:11], v104 offset:8704
	ds_read_b128 v[12:15], v104 offset:13056
	ds_read_b128 v[16:19], v105 offset:34816
	ds_read_b128 v[20:23], v105 offset:39168
	ds_read_b128 v[24:27], v105 offset:43520
	ds_read_b128 v[28:31], v105 offset:47872
	s_waitcnt lgkmcnt(3)
	v_mfma_f32_16x16x32_bf16 v[32:35], v[16:19], v[0:3], 0
	s_waitcnt lgkmcnt(2)
	v_mfma_f32_16x16x32_bf16 v[36:39], v[20:23], v[0:3], 0
	s_waitcnt lgkmcnt(1)
	v_mfma_f32_16x16x32_bf16 v[40:43], v[24:27], v[0:3], 0
	s_waitcnt lgkmcnt(0)
	v_mfma_f32_16x16x32_bf16 v[0:3], v[28:31], v[0:3], 0
	v_mfma_f32_16x16x32_bf16 v[44:47], v[16:19], v[4:7], 0
	v_mfma_f32_16x16x32_bf16 v[48:51], v[20:23], v[4:7], 0
	v_mfma_f32_16x16x32_bf16 v[52:55], v[24:27], v[4:7], 0
	v_mfma_f32_16x16x32_bf16 v[4:7], v[28:31], v[4:7], 0
	v_mfma_f32_16x16x32_bf16 v[56:59], v[16:19], v[8:11], 0
	v_mfma_f32_16x16x32_bf16 v[106:109], v[20:23], v[8:11], 0
	v_mfma_f32_16x16x32_bf16 v[110:113], v[24:27], v[8:11], 0
	v_mfma_f32_16x16x32_bf16 v[8:11], v[28:31], v[8:11], 0
	v_mfma_f32_16x16x32_bf16 v[16:19], v[16:19], v[12:15], 0
	v_mfma_f32_16x16x32_bf16 v[20:23], v[20:23], v[12:15], 0
	v_mfma_f32_16x16x32_bf16 v[24:27], v[24:27], v[12:15], 0
	v_mfma_f32_16x16x32_bf16 v[12:15], v[28:31], v[12:15], 0
	ds_read_b128 v[28:31], v104 offset:64
	ds_read_b128 v[114:117], v104 offset:4416
	ds_read_b128 v[118:121], v104 offset:8768
	ds_read_b128 v[122:125], v104 offset:13120
	ds_read_b128 v[126:129], v105 offset:34880
	ds_read_b128 v[130:133], v105 offset:39232
	ds_read_b128 v[134:137], v105 offset:43584
	ds_read_b128 v[138:141], v105 offset:47936
	s_waitcnt lgkmcnt(3)
	v_mfma_f32_16x16x32_bf16 v[32:35], v[126:129], v[28:31], v[32:35]
	s_waitcnt lgkmcnt(2)
	v_mfma_f32_16x16x32_bf16 v[36:39], v[130:133], v[28:31], v[36:39]
	s_waitcnt lgkmcnt(1)
	v_mfma_f32_16x16x32_bf16 v[40:43], v[134:137], v[28:31], v[40:43]
	s_waitcnt lgkmcnt(0)
	v_mfma_f32_16x16x32_bf16 v[0:3], v[138:141], v[28:31], v[0:3]
	v_mfma_f32_16x16x32_bf16 v[28:31], v[126:129], v[114:117], v[44:47]
	v_mfma_f32_16x16x32_bf16 v[44:47], v[130:133], v[114:117], v[48:51]
	v_mfma_f32_16x16x32_bf16 v[48:51], v[134:137], v[114:117], v[52:55]
	v_mfma_f32_16x16x32_bf16 v[4:7], v[138:141], v[114:117], v[4:7]
	v_mfma_f32_16x16x32_bf16 v[52:55], v[126:129], v[118:121], v[56:59]
	v_mfma_f32_16x16x32_bf16 v[56:59], v[130:133], v[118:121], v[106:109]
	v_mfma_f32_16x16x32_bf16 v[106:109], v[134:137], v[118:121], v[110:113]
	v_mfma_f32_16x16x32_bf16 v[8:11], v[138:141], v[118:121], v[8:11]
	v_mfma_f32_16x16x32_bf16 v[16:19], v[126:129], v[122:125], v[16:19]
	v_mfma_f32_16x16x32_bf16 v[20:23], v[130:133], v[122:125], v[20:23]
	v_mfma_f32_16x16x32_bf16 v[24:27], v[134:137], v[122:125], v[24:27]
	v_mfma_f32_16x16x32_bf16 v[12:15], v[138:141], v[122:125], v[12:15]
	ds_read_b128 v[110:113], v104 offset:128
	ds_read_b128 v[114:117], v104 offset:4480
	ds_read_b128 v[118:121], v104 offset:8832
	ds_read_b128 v[122:125], v104 offset:13184
	ds_read_b128 v[126:129], v105 offset:34944
	ds_read_b128 v[130:133], v105 offset:39296
	ds_read_b128 v[134:137], v105 offset:43648
	ds_read_b128 v[138:141], v105 offset:48000
	s_waitcnt lgkmcnt(3)
	v_mfma_f32_16x16x32_bf16 v[32:35], v[126:129], v[110:113], v[32:35]
	s_waitcnt lgkmcnt(2)
	v_mfma_f32_16x16x32_bf16 v[36:39], v[130:133], v[110:113], v[36:39]
	s_waitcnt lgkmcnt(1)
	v_mfma_f32_16x16x32_bf16 v[40:43], v[134:137], v[110:113], v[40:43]
	s_waitcnt lgkmcnt(0)
	v_mfma_f32_16x16x32_bf16 v[0:3], v[138:141], v[110:113], v[0:3]
	v_mfma_f32_16x16x32_bf16 v[28:31], v[126:129], v[114:117], v[28:31]
	v_mfma_f32_16x16x32_bf16 v[110:113], v[130:133], v[114:117], v[44:47]
	v_mfma_f32_16x16x32_bf16 v[142:145], v[134:137], v[114:117], v[48:51]
	v_mfma_f32_16x16x32_bf16 v[4:7], v[138:141], v[114:117], v[4:7]
	v_mfma_f32_16x16x32_bf16 v[114:117], v[126:129], v[118:121], v[52:55]
	v_mfma_f32_16x16x32_bf16 v[146:149], v[130:133], v[118:121], v[56:59]
	v_mfma_f32_16x16x32_bf16 v[106:109], v[134:137], v[118:121], v[106:109]
	v_mfma_f32_16x16x32_bf16 v[8:11], v[138:141], v[118:121], v[8:11]
	v_mfma_f32_16x16x32_bf16 v[118:121], v[126:129], v[122:125], v[16:19]
	v_mfma_f32_16x16x32_bf16 v[126:129], v[130:133], v[122:125], v[20:23]
	v_mfma_f32_16x16x32_bf16 v[130:133], v[134:137], v[122:125], v[24:27]
	v_mfma_f32_16x16x32_bf16 v[122:125], v[138:141], v[122:125], v[12:15]
	s_nop 2
	ds_read_b128 v[12:15], v104 offset:192
	ds_read_b128 v[16:19], v104 offset:4544
	ds_read_b128 v[134:137], v104 offset:8896
	ds_read_b128 v[138:141], v104 offset:13248
	ds_read_b128 v[150:153], v105 offset:35008
	ds_read_b128 v[154:157], v105 offset:39360
	ds_read_b128 v[158:161], v105 offset:43712
	ds_read_b128 v[176:179], v105 offset:48064
	s_waitcnt lgkmcnt(1)
	v_mfma_f32_16x16x32_bf16 v[20:23], v[158:161], v[134:137], v[106:109]
	s_nop 2
	v_add_u32_e32 v106, s33, v82
	v_ashrrev_i32_e32 v107, 31, v106
	v_lshlrev_b64 v[106:107], 13, v[106:107]
	v_mfma_f32_16x16x32_bf16 v[52:55], v[158:161], v[12:15], v[40:43]
	v_mfma_f32_16x16x32_bf16 v[40:43], v[154:157], v[16:19], v[110:113]
	s_nop 2
	v_lshl_add_u64 v[110:111], s[0:1], 0, v[106:107]
	v_lshl_add_u64 v[110:111], v[110:111], 0, v[76:77]
	v_mfma_f32_16x16x32_bf16 v[180:183], v[150:153], v[12:15], v[32:35]
	s_waitcnt vmcnt(0)
	v_mov_b32_e32 v71, v234
	v_mov_b32_e32 v106, v240
	v_mov_b32_e32 v107, v241
	v_mov_b32_e32 v108, v242
	v_mov_b32_e32 v109, v243
	v_mov_b32_e32 v112, v184
	v_mov_b32_e32 v113, v185
	v_lshlrev_b32_e32 v73, 16, v112
	s_nop 5
	v_fma_f32 v75, v180, v106, v71
	v_mul_f32_e32 v73, v75, v73
	v_and_b32_e32 v75, 0xffff0000, v112
	v_fma_f32 v106, v181, v107, v71
	v_mul_f32_e32 v75, v106, v75
	v_lshlrev_b32_e32 v106, 16, v113
	v_fma_f32 v107, v182, v108, v71
	v_mul_f32_e32 v107, v107, v106
	v_and_b32_e32 v106, 0xffff0000, v113
	v_fma_f32 v108, v183, v109, v71
	v_mul_f32_e32 v108, v108, v106
	v_cvt_pk_bf16_f32 v106, v73, v75
	v_cvt_pk_bf16_f32 v107, v107, v108
	global_store_dwordx2 v[110:111], v[106:107], off
	s_nop 0
	v_mfma_f32_16x16x32_bf16 v[56:59], v[154:157], v[12:15], v[36:39]
	v_mov_b32_e32 v106, v244
	v_mov_b32_e32 v107, v245
	v_mov_b32_e32 v108, v246
	v_mov_b32_e32 v109, v247
	v_mov_b32_e32 v112, v186
	v_mov_b32_e32 v113, v187
	v_lshlrev_b32_e32 v73, 16, v112
	s_nop 5
	v_fma_f32 v56, v56, v106, v71
	v_mul_f32_e32 v56, v56, v73
	v_and_b32_e32 v73, 0xffff0000, v112
	v_fma_f32 v57, v57, v107, v71
	v_mul_f32_e32 v57, v57, v73
	v_lshlrev_b32_e32 v73, 16, v113
	v_fma_f32 v58, v58, v108, v71
	v_mul_f32_e32 v58, v58, v73
	v_and_b32_e32 v73, 0xffff0000, v113
	v_fma_f32 v59, v59, v109, v71
	v_mul_f32_e32 v59, v59, v73
	v_cvt_pk_bf16_f32 v56, v56, v57
	v_cvt_pk_bf16_f32 v57, v58, v59
	global_store_dwordx2 v[110:111], v[56:57], off offset:32
	s_nop 0
	s_waitcnt lgkmcnt(0)
	v_mfma_f32_16x16x32_bf16 v[48:51], v[176:179], v[12:15], v[0:3]
	v_mov_b32_e32 v56, v248
	v_mov_b32_e32 v57, v249
	v_mov_b32_e32 v58, v250
	v_mov_b32_e32 v59, v251
	v_mov_b32_e32 v106, v188
	v_mov_b32_e32 v107, v189
	v_fma_f32 v52, v52, v56, v71
	v_and_b32_e32 v56, 0xffff0000, v106
	v_fma_f32 v53, v53, v57, v71
	v_lshlrev_b32_e32 v73, 16, v106
	v_mul_f32_e32 v53, v53, v56
	v_lshlrev_b32_e32 v56, 16, v107
	v_fma_f32 v54, v54, v58, v71
	v_mul_f32_e32 v52, v52, v73
	v_mul_f32_e32 v54, v54, v56
	v_and_b32_e32 v56, 0xffff0000, v107
	v_fma_f32 v55, v55, v59, v71
	v_mul_f32_e32 v55, v55, v56
	v_cvt_pk_bf16_f32 v52, v52, v53
	v_cvt_pk_bf16_f32 v53, v54, v55
	global_store_dwordx2 v[110:111], v[52:53], off offset:64
	s_nop 0
	v_mfma_f32_16x16x32_bf16 v[44:47], v[150:153], v[16:19], v[28:31]
	v_mov_b32_e32 v52, v216
	v_mov_b32_e32 v53, v217
	v_mov_b32_e32 v54, v252
	v_mov_b32_e32 v55, v253
	v_mov_b32_e32 v56, v190
	v_mov_b32_e32 v57, v191
	v_fma_f32 v48, v48, v52, v71
	v_lshlrev_b32_e32 v58, 16, v56
	v_and_b32_e32 v52, 0xffff0000, v56
	v_fma_f32 v49, v49, v53, v71
	v_mul_f32_e32 v48, v48, v58
	v_mul_f32_e32 v49, v49, v52
	v_lshlrev_b32_e32 v52, 16, v57
	v_fma_f32 v50, v50, v54, v71
	v_mul_f32_e32 v50, v50, v52
	v_and_b32_e32 v52, 0xffff0000, v57
	v_fmac_f32_e32 v71, v51, v55
	v_cvt_pk_bf16_f32 v48, v48, v49
	v_mul_f32_e32 v51, v71, v52
	v_cvt_pk_bf16_f32 v49, v50, v51
	global_store_dwordx2 v[110:111], v[48:49], off offset:96
	v_add_u32_e32 v48, s33, v99
	v_ashrrev_i32_e32 v49, 31, v48
	v_lshlrev_b64 v[48:49], 13, v[48:49]
	v_lshl_add_u64 v[52:53], s[0:1], 0, v[48:49]
	v_lshl_add_u64 v[52:53], v[52:53], 0, v[76:77]
	v_mfma_f32_16x16x32_bf16 v[36:39], v[158:161], v[16:19], v[142:145]
	v_mov_b32_e32 v56, v235
	v_mov_b32_e32 v48, v240
	v_mov_b32_e32 v49, v241
	v_mov_b32_e32 v50, v242
	v_mov_b32_e32 v51, v243
	v_mov_b32_e32 v54, v192
	v_mov_b32_e32 v55, v193
	v_fma_f32 v44, v44, v48, v56
	v_and_b32_e32 v48, 0xffff0000, v54
	v_fma_f32 v45, v45, v49, v56
	v_lshlrev_b32_e32 v57, 16, v54
	v_mul_f32_e32 v45, v45, v48
	v_lshlrev_b32_e32 v48, 16, v55
	v_fma_f32 v46, v46, v50, v56
	v_mul_f32_e32 v44, v44, v57
	v_mul_f32_e32 v46, v46, v48
	v_and_b32_e32 v48, 0xffff0000, v55
	v_fma_f32 v47, v47, v51, v56
	v_mul_f32_e32 v47, v47, v48
	v_cvt_pk_bf16_f32 v44, v44, v45
	v_cvt_pk_bf16_f32 v45, v46, v47
	global_store_dwordx2 v[52:53], v[44:45], off
	s_nop 0
	v_mfma_f32_16x16x32_bf16 v[32:35], v[176:179], v[16:19], v[4:7]
	v_mov_b32_e32 v44, v244
	v_mov_b32_e32 v45, v245
	v_mov_b32_e32 v46, v246
	v_mov_b32_e32 v47, v247
	v_mov_b32_e32 v48, v194
	v_mov_b32_e32 v49, v195
	v_fma_f32 v40, v40, v44, v56
	v_and_b32_e32 v44, 0xffff0000, v48
	v_fma_f32 v41, v41, v45, v56
	v_lshlrev_b32_e32 v50, 16, v48
	v_mul_f32_e32 v41, v41, v44
	v_lshlrev_b32_e32 v44, 16, v49
	v_fma_f32 v42, v42, v46, v56
	v_mul_f32_e32 v40, v40, v50
	v_mul_f32_e32 v42, v42, v44
	v_and_b32_e32 v44, 0xffff0000, v49
	v_fma_f32 v43, v43, v47, v56
	v_mul_f32_e32 v43, v43, v44
	v_cvt_pk_bf16_f32 v40, v40, v41
	v_cvt_pk_bf16_f32 v41, v42, v43
	global_store_dwordx2 v[52:53], v[40:41], off offset:32
	s_nop 0
	v_mfma_f32_16x16x32_bf16 v[28:31], v[150:153], v[134:137], v[114:117]
	v_mov_b32_e32 v40, v248
	v_mov_b32_e32 v41, v249
	v_mov_b32_e32 v42, v250
	v_mov_b32_e32 v43, v251
	v_mov_b32_e32 v44, v196
	v_mov_b32_e32 v45, v197
	v_fma_f32 v36, v36, v40, v56
	v_and_b32_e32 v40, 0xffff0000, v44
	v_fma_f32 v37, v37, v41, v56
	v_lshlrev_b32_e32 v46, 16, v44
	v_mul_f32_e32 v37, v37, v40
	v_lshlrev_b32_e32 v40, 16, v45
	v_fma_f32 v38, v38, v42, v56
	v_mul_f32_e32 v36, v36, v46
	v_mul_f32_e32 v38, v38, v40
	v_and_b32_e32 v40, 0xffff0000, v45
	v_fma_f32 v39, v39, v43, v56
	v_mul_f32_e32 v39, v39, v40
	v_cvt_pk_bf16_f32 v36, v36, v37
	v_cvt_pk_bf16_f32 v37, v38, v39
	global_store_dwordx2 v[52:53], v[36:37], off offset:64
	s_nop 0
	v_mfma_f32_16x16x32_bf16 v[24:27], v[154:157], v[134:137], v[146:149]
	v_mov_b32_e32 v36, v216
	v_mov_b32_e32 v37, v217
	v_mov_b32_e32 v38, v252
	v_mov_b32_e32 v39, v253
	v_mov_b32_e32 v40, v198
	v_mov_b32_e32 v41, v199
	v_fma_f32 v32, v32, v36, v56
	v_lshlrev_b32_e32 v42, 16, v40
	v_and_b32_e32 v36, 0xffff0000, v40
	v_fma_f32 v33, v33, v37, v56
	v_mul_f32_e32 v32, v32, v42
	v_mul_f32_e32 v33, v33, v36
	v_lshlrev_b32_e32 v36, 16, v41
	v_fma_f32 v34, v34, v38, v56
	v_mul_f32_e32 v34, v34, v36
	v_and_b32_e32 v36, 0xffff0000, v41
	v_fmac_f32_e32 v56, v35, v39
	v_cvt_pk_bf16_f32 v32, v32, v33
	v_mul_f32_e32 v35, v56, v36
	v_cvt_pk_bf16_f32 v33, v34, v35
	global_store_dwordx2 v[52:53], v[32:33], off offset:96
	v_add_u32_e32 v32, s33, v100
	v_ashrrev_i32_e32 v33, 31, v32
	v_lshlrev_b64 v[32:33], 13, v[32:33]
	v_lshl_add_u64 v[36:37], s[0:1], 0, v[32:33]
	v_lshl_add_u64 v[36:37], v[36:37], 0, v[76:77]
	v_mfma_f32_16x16x32_bf16 v[16:19], v[176:179], v[134:137], v[8:11]
	v_mov_b32_e32 v40, v237
	v_mov_b32_e32 v32, v240
	v_mov_b32_e32 v33, v241
	v_mov_b32_e32 v34, v242
	v_mov_b32_e32 v35, v243
	v_mov_b32_e32 v38, v200
	v_mov_b32_e32 v39, v201
	v_fma_f32 v28, v28, v32, v40
	v_and_b32_e32 v32, 0xffff0000, v38
	v_fma_f32 v29, v29, v33, v40
	v_lshlrev_b32_e32 v41, 16, v38
	v_mul_f32_e32 v29, v29, v32
	v_lshlrev_b32_e32 v32, 16, v39
	v_fma_f32 v30, v30, v34, v40
	v_mul_f32_e32 v28, v28, v41
	v_mul_f32_e32 v30, v30, v32
	v_and_b32_e32 v32, 0xffff0000, v39
	v_fma_f32 v31, v31, v35, v40
	v_mul_f32_e32 v31, v31, v32
	v_cvt_pk_bf16_f32 v28, v28, v29
	v_cvt_pk_bf16_f32 v29, v30, v31
	global_store_dwordx2 v[36:37], v[28:29], off
	s_nop 0
	v_mfma_f32_16x16x32_bf16 v[12:15], v[150:153], v[138:141], v[118:121]
	v_mov_b32_e32 v28, v244
	v_mov_b32_e32 v29, v245
	v_mov_b32_e32 v30, v246
	v_mov_b32_e32 v31, v247
	v_mov_b32_e32 v32, v202
	v_mov_b32_e32 v33, v203
	v_fma_f32 v24, v24, v28, v40
	v_and_b32_e32 v28, 0xffff0000, v32
	v_fma_f32 v25, v25, v29, v40
	v_lshlrev_b32_e32 v34, 16, v32
	v_mul_f32_e32 v25, v25, v28
	v_lshlrev_b32_e32 v28, 16, v33
	v_fma_f32 v26, v26, v30, v40
	v_mul_f32_e32 v24, v24, v34
	v_mul_f32_e32 v26, v26, v28
	v_and_b32_e32 v28, 0xffff0000, v33
	v_fma_f32 v27, v27, v31, v40
	v_mul_f32_e32 v27, v27, v28
	v_cvt_pk_bf16_f32 v24, v24, v25
	v_cvt_pk_bf16_f32 v25, v26, v27
	global_store_dwordx2 v[36:37], v[24:25], off offset:32
	s_nop 0
	v_mfma_f32_16x16x32_bf16 v[8:11], v[154:157], v[138:141], v[126:129]
	v_mov_b32_e32 v24, v248
	v_mov_b32_e32 v25, v249
	v_mov_b32_e32 v26, v250
	v_mov_b32_e32 v27, v251
	v_mov_b32_e32 v28, v204
	v_mov_b32_e32 v29, v205
	v_fma_f32 v20, v20, v24, v40
	v_and_b32_e32 v24, 0xffff0000, v28
	v_fma_f32 v21, v21, v25, v40
	v_lshlrev_b32_e32 v30, 16, v28
	v_mul_f32_e32 v21, v21, v24
	v_lshlrev_b32_e32 v24, 16, v29
	v_fma_f32 v22, v22, v26, v40
	v_mul_f32_e32 v20, v20, v30
	v_mul_f32_e32 v22, v22, v24
	v_and_b32_e32 v24, 0xffff0000, v29
	v_fma_f32 v23, v23, v27, v40
	v_mul_f32_e32 v23, v23, v24
	v_cvt_pk_bf16_f32 v20, v20, v21
	v_cvt_pk_bf16_f32 v21, v22, v23
	global_store_dwordx2 v[36:37], v[20:21], off offset:64
	s_nop 0
	v_mfma_f32_16x16x32_bf16 v[4:7], v[158:161], v[138:141], v[130:133]
	v_mov_b32_e32 v20, v216
	v_mov_b32_e32 v21, v217
	v_mov_b32_e32 v22, v252
	v_mov_b32_e32 v23, v253
	v_mov_b32_e32 v24, v206
	v_mov_b32_e32 v25, v207
	v_fma_f32 v16, v16, v20, v40
	v_lshlrev_b32_e32 v26, 16, v24
	v_and_b32_e32 v20, 0xffff0000, v24
	v_fma_f32 v17, v17, v21, v40
	v_mul_f32_e32 v16, v16, v26
	v_mul_f32_e32 v17, v17, v20
	v_lshlrev_b32_e32 v20, 16, v25
	v_fma_f32 v18, v18, v22, v40
	v_mul_f32_e32 v18, v18, v20
	v_and_b32_e32 v20, 0xffff0000, v25
	v_fmac_f32_e32 v40, v19, v23
	v_cvt_pk_bf16_f32 v16, v16, v17
	v_mul_f32_e32 v19, v40, v20
	v_cvt_pk_bf16_f32 v17, v18, v19
	global_store_dwordx2 v[36:37], v[16:17], off offset:96
	v_add_u32_e32 v16, s33, v101
	v_ashrrev_i32_e32 v17, 31, v16
	v_lshlrev_b64 v[16:17], 13, v[16:17]
	v_lshl_add_u64 v[20:21], s[0:1], 0, v[16:17]
	v_lshl_add_u64 v[20:21], v[20:21], 0, v[76:77]
	v_mfma_f32_16x16x32_bf16 v[0:3], v[176:179], v[138:141], v[122:125]
	v_mov_b32_e32 v22, v228
	v_mov_b32_e32 v16, v240
	v_mov_b32_e32 v17, v241
	v_mov_b32_e32 v18, v242
	v_mov_b32_e32 v19, v243
	v_mov_b32_e32 v24, v208
	v_mov_b32_e32 v25, v209
	v_fma_f32 v12, v12, v16, v22
	v_and_b32_e32 v16, 0xffff0000, v24
	v_fma_f32 v13, v13, v17, v22
	v_lshlrev_b32_e32 v23, 16, v24
	v_mul_f32_e32 v13, v13, v16
	v_lshlrev_b32_e32 v16, 16, v25
	v_fma_f32 v14, v14, v18, v22
	v_mul_f32_e32 v12, v12, v23
	v_mul_f32_e32 v14, v14, v16
	v_and_b32_e32 v16, 0xffff0000, v25
	v_fma_f32 v15, v15, v19, v22
	v_mul_f32_e32 v15, v15, v16
	v_cvt_pk_bf16_f32 v12, v12, v13
	v_cvt_pk_bf16_f32 v13, v14, v15
	global_store_dwordx2 v[20:21], v[12:13], off
	s_nop 0
	v_mov_b32_e32 v12, v244
	v_mov_b32_e32 v13, v245
	v_mov_b32_e32 v14, v246
	v_mov_b32_e32 v15, v247
	v_mov_b32_e32 v16, v210
	v_mov_b32_e32 v17, v211
	v_fma_f32 v8, v8, v12, v22
	v_and_b32_e32 v12, 0xffff0000, v16
	v_fma_f32 v9, v9, v13, v22
	v_lshlrev_b32_e32 v18, 16, v16
	v_mul_f32_e32 v9, v9, v12
	v_lshlrev_b32_e32 v12, 16, v17
	v_fma_f32 v10, v10, v14, v22
	v_mul_f32_e32 v8, v8, v18
	v_mul_f32_e32 v10, v10, v12
	v_and_b32_e32 v12, 0xffff0000, v17
	v_fma_f32 v11, v11, v15, v22
	v_mul_f32_e32 v11, v11, v12
	v_cvt_pk_bf16_f32 v8, v8, v9
	v_cvt_pk_bf16_f32 v9, v10, v11
	global_store_dwordx2 v[20:21], v[8:9], off offset:32
	s_nop 0
	v_mov_b32_e32 v8, v248
	v_mov_b32_e32 v9, v249
	v_mov_b32_e32 v10, v250
	v_mov_b32_e32 v11, v251
	v_mov_b32_e32 v12, v212
	v_mov_b32_e32 v13, v213
	v_fma_f32 v4, v4, v8, v22
	v_and_b32_e32 v8, 0xffff0000, v12
	v_fma_f32 v5, v5, v9, v22
	v_lshlrev_b32_e32 v14, 16, v12
	v_mul_f32_e32 v5, v5, v8
	v_lshlrev_b32_e32 v8, 16, v13
	v_fma_f32 v6, v6, v10, v22
	v_mul_f32_e32 v4, v4, v14
	v_mul_f32_e32 v6, v6, v8
	v_and_b32_e32 v8, 0xffff0000, v13
	v_fma_f32 v7, v7, v11, v22
	v_mul_f32_e32 v7, v7, v8
	v_cvt_pk_bf16_f32 v4, v4, v5
	v_cvt_pk_bf16_f32 v5, v6, v7
	global_store_dwordx2 v[20:21], v[4:5], off offset:64
	s_nop 0
	v_mov_b32_e32 v4, v216
	v_mov_b32_e32 v5, v217
	v_mov_b32_e32 v6, v252
	v_mov_b32_e32 v7, v253
	v_mov_b32_e32 v8, v214
	v_mov_b32_e32 v9, v215
	v_fma_f32 v0, v0, v4, v22
	v_and_b32_e32 v4, 0xffff0000, v8
	v_fma_f32 v1, v1, v5, v22
	v_lshlrev_b32_e32 v10, 16, v8
	v_mul_f32_e32 v1, v1, v4
	v_lshlrev_b32_e32 v4, 16, v9
	v_fma_f32 v2, v2, v6, v22
	v_mul_f32_e32 v0, v0, v10
	v_mul_f32_e32 v2, v2, v4
	v_and_b32_e32 v4, 0xffff0000, v9
	v_fmac_f32_e32 v22, v3, v7
	v_mul_f32_e32 v3, v22, v4
	v_cvt_pk_bf16_f32 v0, v0, v1
	v_cvt_pk_bf16_f32 v1, v2, v3
	global_store_dwordx2 v[20:21], v[0:1], off offset:96
	s_barrier
	s_cbranch_scc1 .LBB0_688
	v_readlane_b32 s69, v255, 16
	v_readlane_b32 s76, v255, 15
	v_readlane_b32 s79, v255, 14
